# v31 plus grid-barrier and queue spin loops polling without s_sleep (shorter release detection latency)
# baseline (speedup 1.0000x reference)
; __device__ __forceinline__ unsigned xb_ld(unsigned* p)              { return __hip_atomic_load(p, __ATOMIC_RELAXED, __HIP_MEMORY_SCOPE_AGENT); }
; __device__ __forceinline__ void xcd_barrier_complete(unsigned* bar, unsigned x, unsigned& nloc, unsigned& nx) {
;     const unsigned G = gridDim.x * gridDim.y * gridDim.z;
;     unsigned sum, cnt, mine, sp = 0u;
;     for (;;) {
;         sum = 0u; cnt = 0u; mine = 0u;
; #pragma unroll
;         for (unsigned j = 0; j < 16; ++j) { const unsigned c = xb_ld(&bar[XB_XCNT(j)]); sum += c; cnt += (c > 0u) ? 1u : 0u; mine = (j == x) ? c : mine; }
;         if (sum == G) break;
;         __builtin_amdgcn_s_sleep(1);
;         if ((++sp & 255u) == 0u) { if (xb_ld(&bar[XB_TMO])) break; if (sp > XB_SPIN_CAP) { atomicAdd(&bar[XB_TMO], 1u); break; } }
;     }
;     nloc = mine > 0u ? mine : 1u; nx = cnt > 0u ? cnt : 1u;
; }
.LBB0_85:
	global_load_dword v16, v1, s[90:91] offset:1024 sc1
	s_waitcnt lgkmcnt(0)
	global_load_dword v0, v1, s[90:91] offset:1280 sc1
	global_load_dword v2, v1, s[90:91] offset:1536 sc1
	global_load_dword v3, v1, s[90:91] offset:1792 sc1
	global_load_dword v4, v1, s[90:91] offset:2048 sc1
	global_load_dword v5, v1, s[90:91] offset:2304 sc1
	global_load_dword v6, v1, s[90:91] offset:2560 sc1
	global_load_dword v7, v1, s[90:91] offset:2816 sc1
	global_load_dword v8, v1, s[90:91] offset:3072 sc1
	global_load_dword v9, v1, s[90:91] offset:3328 sc1
	global_load_dword v10, v1, s[90:91] offset:3584 sc1
	global_load_dword v11, v1, s[90:91] offset:3840 sc1
	global_load_dword v12, v1, s[2:3] sc1
	global_load_dword v13, v1, s[4:5] sc1
	global_load_dword v14, v1, s[6:7] sc1
	global_load_dword v15, v1, s[8:9] sc1
	s_mov_b64 s[10:11], -1
	s_mov_b64 s[12:13], -1
	s_waitcnt vmcnt(14)
	v_add_u32_e32 v17, v0, v16
	s_waitcnt vmcnt(13)
	v_add_u32_e32 v17, v17, v2
	s_waitcnt vmcnt(12)
	v_add_u32_e32 v17, v17, v3
	s_waitcnt vmcnt(11)
	v_add_u32_e32 v17, v17, v4
	s_waitcnt vmcnt(10)
	v_add_u32_e32 v17, v17, v5
	s_waitcnt vmcnt(9)
	v_add_u32_e32 v17, v17, v6
	s_waitcnt vmcnt(8)
	v_add_u32_e32 v17, v17, v7
	s_waitcnt vmcnt(7)
	v_add_u32_e32 v17, v17, v8
	s_waitcnt vmcnt(6)
	v_add_u32_e32 v17, v17, v9
	s_waitcnt vmcnt(5)
	v_add_u32_e32 v17, v17, v10
	s_waitcnt vmcnt(4)
	v_add_u32_e32 v17, v17, v11
	s_waitcnt vmcnt(3)
	v_add_u32_e32 v17, v17, v12
	s_waitcnt vmcnt(2)
	v_add_u32_e32 v17, v17, v13
	s_waitcnt vmcnt(1)
	v_add_u32_e32 v17, v17, v14
	s_waitcnt vmcnt(0)
	v_add_u32_e32 v17, v17, v15
	v_cmp_eq_u32_e32 vcc, s68, v17
	s_cbranch_vccnz .LBB0_84
	s_and_b32 s10, s16, 0xff
	s_cmp_eq_u32 s10, 0
	s_mov_b64 s[10:11], -1
	s_mov_b64 s[14:15], -1
	s_cbranch_scc1 .LBB0_89
	s_and_b64 vcc, exec, s[14:15]
	s_cbranch_vccz .LBB0_84

; __device__ __forceinline__ unsigned xb_ld(unsigned* p)              { return __hip_atomic_load(p, __ATOMIC_RELAXED, __HIP_MEMORY_SCOPE_AGENT); }
; __device__ __forceinline__ unsigned xb_add(unsigned* p, unsigned v) { return __hip_atomic_fetch_add(p, v, __ATOMIC_RELAXED, __HIP_MEMORY_SCOPE_AGENT); }
; #define XB_SPIN(cond, bar) do { unsigned _sp = 0; while (cond) { __builtin_amdgcn_s_sleep(1); \
;     if ((++_sp & 255u) == 0u) { if (xb_ld(&(bar)[XB_TMO])) break; if (_sp > XB_SPIN_CAP) { atomicAdd(&(bar)[XB_TMO], 1u); break; } } } } while (0)
; __device__ __forceinline__ void xcd_barrier(const XcdBarrier& b) {
;     ...
;             else XB_SPIN(xb_ld(&bar[XB_TOPGEN]) == tg, bar);
;             __builtin_amdgcn_fence(__ATOMIC_ACQUIRE, "agent");
;             xb_add(&bar[XB_XGEN(b.x)], 1u);
;             asm volatile("s_waitcnt vmcnt(0)" ::: "memory");
;         } else {
;             XB_SPIN(xb_ld(&bar[XB_XGEN(b.x)]) == gen, bar);
.LBB0_99:
	s_and_b32 s16, s20, 0xff
	s_mov_b64 s[14:15], -1
	s_cmp_lg_u32 s16, 0
	s_mov_b64 s[18:19], -1
	s_cbranch_scc0 .LBB0_102
	s_and_b64 vcc, exec, s[18:19]
	s_cbranch_vccz .LBB0_98

; __device__ __forceinline__ unsigned xb_ld(unsigned* p)              { return __hip_atomic_load(p, __ATOMIC_RELAXED, __HIP_MEMORY_SCOPE_AGENT); }
; __device__ __forceinline__ unsigned xb_add(unsigned* p, unsigned v) { return __hip_atomic_fetch_add(p, v, __ATOMIC_RELAXED, __HIP_MEMORY_SCOPE_AGENT); }
; #define XB_SPIN(cond, bar) do { unsigned _sp = 0; while (cond) { __builtin_amdgcn_s_sleep(1); \
;     if ((++_sp & 255u) == 0u) { if (xb_ld(&(bar)[XB_TMO])) break; if (_sp > XB_SPIN_CAP) { atomicAdd(&(bar)[XB_TMO], 1u); break; } } } } while (0)
; __device__ __forceinline__ void xcd_barrier(const XcdBarrier& b) {
;     ...
;             else XB_SPIN(xb_ld(&bar[XB_TOPGEN]) == tg, bar);
;             __builtin_amdgcn_fence(__ATOMIC_ACQUIRE, "agent");
;             xb_add(&bar[XB_XGEN(b.x)], 1u);
;             asm volatile("s_waitcnt vmcnt(0)" ::: "memory");
;         } else {
;             XB_SPIN(xb_ld(&bar[XB_XGEN(b.x)]) == gen, bar);
.LBB0_113:
	s_and_b32 s18, s22, 0xff
	s_mov_b64 s[16:17], -1
	s_cmp_lg_u32 s18, 0
	s_mov_b64 s[20:21], -1
	s_cbranch_scc0 .LBB0_116
	s_and_b64 vcc, exec, s[20:21]
	s_cbranch_vccz .LBB0_112

; __device__ __forceinline__ unsigned xb_ld(unsigned* p)              { return __hip_atomic_load(p, __ATOMIC_RELAXED, __HIP_MEMORY_SCOPE_AGENT); }
; __device__ __forceinline__ void xcd_barrier_complete(unsigned* bar, unsigned x, unsigned& nloc, unsigned& nx) {
;     const unsigned G = gridDim.x * gridDim.y * gridDim.z;
;     unsigned sum, cnt, mine, sp = 0u;
;     for (;;) {
;         sum = 0u; cnt = 0u; mine = 0u;
; #pragma unroll
;         for (unsigned j = 0; j < 16; ++j) { const unsigned c = xb_ld(&bar[XB_XCNT(j)]); sum += c; cnt += (c > 0u) ? 1u : 0u; mine = (j == x) ? c : mine; }
;         if (sum == G) break;
;         __builtin_amdgcn_s_sleep(1);
;         if ((++sp & 255u) == 0u) { if (xb_ld(&bar[XB_TMO])) break; if (sp > XB_SPIN_CAP) { atomicAdd(&bar[XB_TMO], 1u); break; } }
;     }
;     nloc = mine > 0u ? mine : 1u; nx = cnt > 0u ? cnt : 1u;
; }
.LBB0_244:
	global_load_dword v16, v1, s[90:91] offset:1024 sc1
	global_load_dword v0, v1, s[90:91] offset:1280 sc1
	s_waitcnt lgkmcnt(0)
	global_load_dword v2, v1, s[90:91] offset:1536 sc1
	global_load_dword v3, v1, s[90:91] offset:1792 sc1
	global_load_dword v4, v1, s[90:91] offset:2048 sc1
	global_load_dword v5, v1, s[90:91] offset:2304 sc1
	global_load_dword v6, v1, s[90:91] offset:2560 sc1
	global_load_dword v7, v1, s[90:91] offset:2816 sc1
	global_load_dword v8, v1, s[90:91] offset:3072 sc1
	global_load_dword v9, v1, s[90:91] offset:3328 sc1
	global_load_dword v10, v1, s[90:91] offset:3584 sc1
	global_load_dword v11, v1, s[90:91] offset:3840 sc1
	global_load_dword v12, v1, s[2:3] sc1
	global_load_dword v13, v1, s[4:5] sc1
	global_load_dword v14, v1, s[6:7] sc1
	global_load_dword v15, v1, s[8:9] sc1
	s_mov_b64 s[10:11], -1
	s_mov_b64 s[12:13], -1
	s_waitcnt vmcnt(14)
	v_add_u32_e32 v17, v0, v16
	s_waitcnt vmcnt(13)
	v_add_u32_e32 v17, v17, v2
	s_waitcnt vmcnt(12)
	v_add_u32_e32 v17, v17, v3
	s_waitcnt vmcnt(11)
	v_add_u32_e32 v17, v17, v4
	s_waitcnt vmcnt(10)
	v_add_u32_e32 v17, v17, v5
	s_waitcnt vmcnt(9)
	v_add_u32_e32 v17, v17, v6
	s_waitcnt vmcnt(8)
	v_add_u32_e32 v17, v17, v7
	s_waitcnt vmcnt(7)
	v_add_u32_e32 v17, v17, v8
	s_waitcnt vmcnt(6)
	v_add_u32_e32 v17, v17, v9
	s_waitcnt vmcnt(5)
	v_add_u32_e32 v17, v17, v10
	s_waitcnt vmcnt(4)
	v_add_u32_e32 v17, v17, v11
	s_waitcnt vmcnt(3)
	v_add_u32_e32 v17, v17, v12
	s_waitcnt vmcnt(2)
	v_add_u32_e32 v17, v17, v13
	s_waitcnt vmcnt(1)
	v_add_u32_e32 v17, v17, v14
	s_waitcnt vmcnt(0)
	v_add_u32_e32 v17, v17, v15
	v_cmp_eq_u32_e32 vcc, s68, v17
	s_cbranch_vccnz .LBB0_243
	s_and_b32 s10, s16, 0xff
	s_cmp_eq_u32 s10, 0
	s_mov_b64 s[10:11], -1
	s_mov_b64 s[14:15], -1
	s_cbranch_scc1 .LBB0_248
	s_and_b64 vcc, exec, s[14:15]
	s_cbranch_vccz .LBB0_243

; __global__ void __launch_bounds__(NTHREADS, 2) fwd_kernel(Params prm) {
;     ...
;             if (l == 0 && ffn == 0) { grid.sync();
.LBB0_1085:
	global_load_dword v2, v1, s[2:3] offset:32 sc1
	s_waitcnt vmcnt(0)
	v_and_b32_e32 v2, 0xffff0000, v2
	v_cmp_ne_u32_e32 vcc, v2, v0
	s_or_b64 s[4:5], vcc, s[4:5]
	s_andn2_b64 exec, exec, s[4:5]
	s_cbranch_execnz .LBB0_1085

; __device__ __forceinline__ unsigned xb_ld(unsigned* p)              { return __hip_atomic_load(p, __ATOMIC_RELAXED, __HIP_MEMORY_SCOPE_AGENT); }
; __device__ __forceinline__ void xcd_barrier_complete(unsigned* bar, unsigned x, unsigned& nloc, unsigned& nx) {
;     const unsigned G = gridDim.x * gridDim.y * gridDim.z;
;     unsigned sum, cnt, mine, sp = 0u;
;     for (;;) {
;         sum = 0u; cnt = 0u; mine = 0u;
; #pragma unroll
;         for (unsigned j = 0; j < 16; ++j) { const unsigned c = xb_ld(&bar[XB_XCNT(j)]); sum += c; cnt += (c > 0u) ? 1u : 0u; mine = (j == x) ? c : mine; }
;         if (sum == G) break;
;         __builtin_amdgcn_s_sleep(1);
;         if ((++sp & 255u) == 0u) { if (xb_ld(&bar[XB_TMO])) break; if (sp > XB_SPIN_CAP) { atomicAdd(&bar[XB_TMO], 1u); break; } }
;     }
;     nloc = mine > 0u ? mine : 1u; nx = cnt > 0u ? cnt : 1u;
; }
.LBB0_1111:
	global_load_dword v16, v1, s[90:91] offset:1024 sc1
	global_load_dword v0, v1, s[90:91] offset:1280 sc1
	s_waitcnt lgkmcnt(0)
	global_load_dword v2, v1, s[90:91] offset:1536 sc1
	global_load_dword v3, v1, s[90:91] offset:1792 sc1
	global_load_dword v4, v1, s[90:91] offset:2048 sc1
	global_load_dword v5, v1, s[90:91] offset:2304 sc1
	global_load_dword v6, v1, s[90:91] offset:2560 sc1
	global_load_dword v7, v1, s[90:91] offset:2816 sc1
	global_load_dword v8, v1, s[90:91] offset:3072 sc1
	global_load_dword v9, v1, s[90:91] offset:3328 sc1
	global_load_dword v10, v1, s[90:91] offset:3584 sc1
	global_load_dword v11, v1, s[90:91] offset:3840 sc1
	global_load_dword v12, v1, s[2:3] sc1
	global_load_dword v13, v1, s[4:5] sc1
	global_load_dword v14, v1, s[6:7] sc1
	global_load_dword v15, v1, s[10:11] sc1
	s_mov_b64 s[12:13], -1
	s_mov_b64 s[14:15], -1
	s_waitcnt vmcnt(14)
	v_add_u32_e32 v17, v0, v16
	s_waitcnt vmcnt(13)
	v_add_u32_e32 v17, v17, v2
	s_waitcnt vmcnt(12)
	v_add_u32_e32 v17, v17, v3
	s_waitcnt vmcnt(11)
	v_add_u32_e32 v17, v17, v4
	s_waitcnt vmcnt(10)
	v_add_u32_e32 v17, v17, v5
	s_waitcnt vmcnt(9)
	v_add_u32_e32 v17, v17, v6
	s_waitcnt vmcnt(8)
	v_add_u32_e32 v17, v17, v7
	s_waitcnt vmcnt(7)
	v_add_u32_e32 v17, v17, v8
	s_waitcnt vmcnt(6)
	v_add_u32_e32 v17, v17, v9
	s_waitcnt vmcnt(5)
	v_add_u32_e32 v17, v17, v10
	s_waitcnt vmcnt(4)
	v_add_u32_e32 v17, v17, v11
	s_waitcnt vmcnt(3)
	v_add_u32_e32 v17, v17, v12
	s_waitcnt vmcnt(2)
	v_add_u32_e32 v17, v17, v13
	s_waitcnt vmcnt(1)
	v_add_u32_e32 v17, v17, v14
	s_waitcnt vmcnt(0)
	v_add_u32_e32 v17, v17, v15
	v_cmp_eq_u32_e32 vcc, s68, v17
	s_cbranch_vccnz .LBB0_1110
	s_and_b32 s12, s18, 0xff
	s_cmp_eq_u32 s12, 0
	s_mov_b64 s[12:13], -1
	s_mov_b64 s[16:17], -1
	s_cbranch_scc1 .LBB0_1115
	s_and_b64 vcc, exec, s[16:17]
	s_cbranch_vccz .LBB0_1110

; __device__ __forceinline__ unsigned xb_ld(unsigned* p)              { return __hip_atomic_load(p, __ATOMIC_RELAXED, __HIP_MEMORY_SCOPE_AGENT); }
; __device__ __forceinline__ unsigned xb_add(unsigned* p, unsigned v) { return __hip_atomic_fetch_add(p, v, __ATOMIC_RELAXED, __HIP_MEMORY_SCOPE_AGENT); }
; #define XB_SPIN(cond, bar) do { unsigned _sp = 0; while (cond) { __builtin_amdgcn_s_sleep(1); \
;     if ((++_sp & 255u) == 0u) { if (xb_ld(&(bar)[XB_TMO])) break; if (_sp > XB_SPIN_CAP) { atomicAdd(&(bar)[XB_TMO], 1u); break; } } } } while (0)
; __device__ __forceinline__ void xcd_barrier(const XcdBarrier& b) {
;     ...
;             else XB_SPIN(xb_ld(&bar[XB_TOPGEN]) == tg, bar);
;             __builtin_amdgcn_fence(__ATOMIC_ACQUIRE, "agent");
;             xb_add(&bar[XB_XGEN(b.x)], 1u);
;             asm volatile("s_waitcnt vmcnt(0)" ::: "memory");
;         } else {
;             XB_SPIN(xb_ld(&bar[XB_XGEN(b.x)]) == gen, bar);
.LBB0_1139:
	s_and_b32 s20, s24, 0xff
	s_mov_b64 s[18:19], -1
	s_cmp_lg_u32 s20, 0
	s_mov_b64 s[22:23], -1
	s_cbranch_scc0 .LBB0_1142
	s_and_b64 vcc, exec, s[22:23]
	s_cbranch_vccz .LBB0_1138
